# as previous, with the dead per-row store-address VALU pairs and their vcc pad nops deleted instead of replaced by s_nop
# baseline (speedup 1.0000x reference)
; __device__ __forceinline__ float bf2f(unsigned b) { return __uint_as_float(b << 16); }
; __device__ __forceinline__ unsigned pk2(float lo, float hi) { unsigned r; asm("v_cvt_pk_bf16_f32 %0, %1, %2" : "=v"(r) : "v"(lo), "v"(hi)); return r; }
; __device__ __forceinline__ float gelu_t(float x) { return x * __builtin_amdgcn_rcpf(1.f + __expf(-1.5957691216057308f * (x + 0.044715f * x * x * x))); }
; __device__ __forceinline__ void act_item(int item, u16* UP, const u16* HALO, const float* sconv, const float* wconv, const float* bconv, float* out, int lane) {
;     ...
; #pragma unroll
;         for (int t = 0; t < 16; ++t) {
;             const int row = rb * 64 + tb + t;
;             if (sample && (t & 3) == 0) { const int ns = (row - TP) >> 2; const float* s0 = sconv + (size_t)ns * 2 * FF2;
;                 const f32x2 a = *(const f32x2*)(s0 + j0), b = *(const f32x2*)(s0 + FF + j0), c = *(const f32x2*)(s0 + FF2 + j0), dd = *(const f32x2*)(s0 + FF2 + FF + j0);
;                 g2[0] = a.x; g2[1] = a.y; v2[0] = b.x; v2[1] = b.y; g1[0] = c.x; g1[1] = c.y; v1[0] = dd.x; v1[1] = dd.y; }
;             const float g0[2] = {bf2f(gw[t] & 0xffffu), bf2f(gw[t] >> 16)}, v0[2] = {bf2f(vw[t] & 0xffffu), bf2f(vw[t] >> 16)};
;             float res[2];
; #pragma unroll
;             for (int p = 0; p < 2; ++p) { const float cgv = bg[p] + wgt[0][p] * g2[p] + wgt[1][p] * g1[p] + wgt[2][p] * g0[p];
;                 const float cvv = bv[p] + wvl[0][p] * v2[p] + wvl[1][p] * v1[p] + wvl[2][p] * v0[p]; res[p] = gelu_t(cgv) * cvv;
;                 g2[p] = g1[p]; g1[p] = g0[p]; v2[p] = v1[p]; v1[p] = v0[p]; }
;             *(unsigned*)(UP + (size_t)row * FF2 + j0) = pk2(res[0], res[1]);
.LBB0_777:
	s_waitcnt vmcnt(0)
	s_add_u32 s100, s64, 0x4300000
	s_addc_u32 s101, s65, 0
	v_lshlrev_b32_e32 v62, 16, v47
	v_and_b32_e32 v63, 0xffff0000, v47
	v_lshlrev_b32_e32 v89, 16, v46
	v_and_b32_e32 v90, 0xffff0000, v46
	v_pk_fma_f32 v[46:47], v[4:5], v[48:49], v[16:17]
	v_pk_fma_f32 v[48:49], v[6:7], v[50:51], v[18:19]
	v_pk_fma_f32 v[46:47], v[8:9], v[52:53], v[46:47]
	v_pk_fma_f32 v[48:49], v[10:11], v[54:55], v[48:49]
	v_fma_f32 v46, v12, v62, v46
	v_fmac_f32_e32 v47, v13, v63
	v_mul_f32_e32 v50, 0x3d372713, v46
	v_mul_f32_e32 v51, 0x3d372713, v47
	v_mul_f32_e32 v50, v46, v50
	v_mul_f32_e32 v51, v47, v51
	v_fma_f32 v50, v46, v50, v46
	v_fma_f32 v51, v47, v51, v47
	v_mul_f32_e32 v50, 0xbfcc422a, v50
	v_mul_f32_e32 v51, 0xbfcc422a, v51
	v_mul_f32_e32 v50, 0x3fb8aa3b, v50
	v_mul_f32_e32 v51, 0x3fb8aa3b, v51
	v_exp_f32_e32 v50, v50
	v_exp_f32_e32 v51, v51
	v_fma_f32 v48, v14, v89, v48
	v_fmac_f32_e32 v49, v15, v90
	v_add_f32_e32 v50, 1.0, v50
	v_add_f32_e32 v51, 1.0, v51
	v_rcp_f32_e32 v50, v50
	v_rcp_f32_e32 v51, v51
	v_pk_fma_f32 v[60:61], v[6:7], v[54:55], v[18:19]
	v_lshlrev_b32_e32 v54, 16, v57
	v_mul_f32_e32 v46, v46, v50
	v_mul_f32_e32 v47, v47, v51
	v_mul_f32_e32 v46, v48, v46
	v_mul_f32_e32 v47, v49, v47
	v_cvt_pk_bf16_f32 v50, v46, v47
	v_lshlrev_b32_e32 v51, 16, v58
	global_store_dword v44, v50, s[100:101]
	s_add_u32 s100, s100, 0x2c00
	s_addc_u32 s101, s101, 0
	v_lshlrev_b32_e32 v50, 16, v59
	v_and_b32_e32 v49, 0xffff0000, v58
	v_and_b32_e32 v48, 0xffff0000, v59
	v_pk_fma_f32 v[58:59], v[4:5], v[52:53], v[16:17]
	v_and_b32_e32 v52, 0xffff0000, v57
	v_fmac_f32_e32 v59, v9, v63
	v_fmac_f32_e32 v59, v13, v49
	v_fma_f32 v58, v8, v62, v58
	v_mul_f32_e32 v57, 0x3d372713, v59
	v_fmac_f32_e32 v58, v12, v51
	v_mul_f32_e32 v57, v59, v57
	v_lshlrev_b32_e32 v55, 16, v56
	v_and_b32_e32 v53, 0xffff0000, v56
	v_mul_f32_e32 v56, 0x3d372713, v58
	v_fma_f32 v57, v59, v57, v59
	v_mul_f32_e32 v56, v58, v56
	v_mul_f32_e32 v57, 0xbfcc422a, v57
	v_fma_f32 v56, v58, v56, v58
	v_mul_f32_e32 v57, 0x3fb8aa3b, v57
	v_mul_f32_e32 v56, 0xbfcc422a, v56
	v_exp_f32_e32 v57, v57
	v_mul_f32_e32 v56, 0x3fb8aa3b, v56
	v_exp_f32_e32 v56, v56
	v_fma_f32 v60, v10, v89, v60
	v_add_f32_e32 v57, 1.0, v57
	v_rcp_f32_e32 v57, v57
	v_add_f32_e32 v56, 1.0, v56
	v_rcp_f32_e32 v56, v56
	v_fmac_f32_e32 v60, v14, v50
	v_mul_f32_e32 v57, v59, v57
	v_fma_f32 v59, v4, v62, v16
	v_fmac_f32_e32 v59, v8, v51
	v_mul_f32_e32 v56, v58, v56
	v_fmac_f32_e32 v59, v12, v55
	v_mul_f32_e32 v56, v60, v56
	v_mul_f32_e32 v60, 0x3d372713, v59
	v_mul_f32_e32 v60, v59, v60
	v_fmac_f32_e32 v61, v11, v90
	v_fma_f32 v60, v59, v60, v59
	v_fmac_f32_e32 v61, v40, v48
	v_mul_f32_e32 v60, 0xbfcc422a, v60
	v_mul_f32_e32 v57, v61, v57
	v_cvt_pk_bf16_f32 v58, v56, v57
	v_mul_f32_e32 v60, 0x3fb8aa3b, v60
	v_exp_f32_e32 v60, v60
	global_store_dword v44, v58, s[100:101]
	s_add_u32 s100, s100, 0x2c00
	s_addc_u32 s101, s101, 0
	v_fma_f32 v58, v5, v63, v17
	v_fmac_f32_e32 v58, v9, v49
	v_fmac_f32_e32 v58, v13, v53
	v_add_f32_e32 v57, 1.0, v60
	v_mul_f32_e32 v60, 0x3d372713, v58
	v_mul_f32_e32 v60, v58, v60
	v_fma_f32 v60, v58, v60, v58
	v_mul_f32_e32 v60, 0xbfcc422a, v60
	v_rcp_f32_e32 v57, v57
	v_mul_f32_e32 v60, 0x3fb8aa3b, v60
	v_exp_f32_e32 v60, v60
	v_fma_f32 v56, v6, v89, v18
	v_fmac_f32_e32 v56, v10, v50
	v_fmac_f32_e32 v56, v14, v54
	v_mul_f32_e32 v57, v59, v57
	v_mul_f32_e32 v56, v56, v57
	v_add_f32_e32 v57, 1.0, v60
	v_rcp_f32_e32 v57, v57
	v_fma_f32 v59, v7, v90, v19
	v_fmac_f32_e32 v59, v42, v48
	v_fmac_f32_e32 v59, v40, v52
	v_mul_f32_e32 v57, v58, v57
	v_mul_f32_e32 v57, v59, v57
	v_cvt_pk_bf16_f32 v58, v56, v57
	v_mov_b32_e32 v62, v55
	global_store_dword v44, v58, s[100:101]
	s_add_u32 s100, s100, 0x2c00
	s_addc_u32 s101, s101, 0
	v_mov_b32_e32 v56, v54
	v_mov_b32_e32 v57, v52
	v_mov_b32_e32 v63, v53
	v_cndmask_b32_e64 v58, 0, 1, s[60:61]
	s_mov_b64 s[68:69], -1
	v_cmp_ne_u32_e64 s[0:1], 1, v58
	s_andn2_b64 vcc, exec, s[60:61]
	v_mov_b64_e32 v[58:59], v[62:63]
	v_mov_b64_e32 v[60:61], v[56:57]
	s_cbranch_vccnz .LBB0_779
	v_mov_b32_e32 v58, v55
	v_mov_b32_e32 v59, v53
	v_mov_b32_e32 v60, v54
	v_mov_b32_e32 v61, v52
	s_mov_b64 s[68:69], 0

; __device__ __forceinline__ unsigned pk2(float lo, float hi) { unsigned r; asm("v_cvt_pk_bf16_f32 %0, %1, %2" : "=v"(r) : "v"(lo), "v"(hi)); return r; }
; __device__ __forceinline__ float gelu_t(float x) { return x * __builtin_amdgcn_rcpf(1.f + __expf(-1.5957691216057308f * (x + 0.044715f * x * x * x))); }
; __device__ __forceinline__ void act_item(int item, u16* UP, const u16* HALO, const float* sconv, const float* wconv, const float* bconv, float* out, int lane) {
;     ...
;             for (int p = 0; p < 2; ++p) { const float cgv = bg[p] + wgt[0][p] * g2[p] + wgt[1][p] * g1[p] + wgt[2][p] * g0[p];
;                 const float cvv = bv[p] + wvl[0][p] * v2[p] + wvl[1][p] * v1[p] + wvl[2][p] * v0[p]; res[p] = gelu_t(cgv) * cvv;
;                 g2[p] = g1[p]; g1[p] = g0[p]; v2[p] = v1[p]; v1[p] = v0[p]; }
;             *(unsigned*)(UP + (size_t)row * FF2 + j0) = pk2(res[0], res[1]);
;             if (!sample) { const int tq = row & 2047; if (tq >= 2046) { float* o = out + O_CONVP + ((size_t)(row >> 11) * 2 + (tq - 2046)) * FF2;
;                     *(f32x2*)(o + j0) = (f32x2){g0[0], g0[1]}; *(f32x2*)(o + FF + j0) = (f32x2){v0[0], v0[1]}; } }
;             else if ((t & 3) >= 2) { const int ns = (row - TP) >> 2; float* o = out + O_CONVS + ((size_t)ns * 2 + ((t & 3) - 2)) * FF2;
;                     *(f32x2*)(o + j0) = (f32x2){g0[0], g0[1]}; *(f32x2*)(o + FF + j0) = (f32x2){v0[0], v0[1]}; }
.LBB0_781:
	v_pk_fma_f32 v[50:51], v[26:27], v[50:51], v[24:25]
	v_pk_fma_f32 v[48:49], v[34:35], v[48:49], v[32:33]
	v_lshlrev_b32_e32 v57, 16, v87
	v_lshlrev_b32_e32 v56, 16, v88
	v_and_b32_e32 v63, 0xffff0000, v87
	v_and_b32_e32 v62, 0xffff0000, v88
	v_pk_fma_f32 v[50:51], v[28:29], v[54:55], v[50:51]
	v_pk_fma_f32 v[48:49], v[36:37], v[52:53], v[48:49]
	v_pk_fma_f32 v[50:51], v[30:31], v[56:57], v[50:51]
	v_pk_fma_f32 v[48:49], v[38:39], v[62:63], v[48:49]
	v_mul_f32_e32 v54, 0x3d372713, v51
	v_mul_f32_e32 v52, 0x3d372713, v49
	v_mul_f32_e32 v54, v51, v54
	v_mul_f32_e32 v52, v49, v52
	v_fma_f32 v54, v51, v54, v51
	v_fma_f32 v52, v49, v52, v49
	v_mul_f32_e32 v54, 0xbfcc422a, v54
	v_mul_f32_e32 v52, 0xbfcc422a, v52
	v_mul_f32_e32 v54, 0x3fb8aa3b, v54
	v_mul_f32_e32 v52, 0x3fb8aa3b, v52
	v_exp_f32_e32 v54, v54
	v_exp_f32_e32 v52, v52
	v_add_f32_e32 v53, 1.0, v54
	v_add_f32_e32 v52, 1.0, v52
	v_rcp_f32_e32 v53, v53
	v_rcp_f32_e32 v52, v52
	v_mul_f32_e32 v51, v51, v53
	v_mul_f32_e32 v49, v49, v52
	v_mul_f32_e32 v50, v50, v51
	v_mul_f32_e32 v48, v48, v49
	v_cvt_pk_bf16_f32 v50, v50, v48
	v_mov_b32_e32 v52, v57
	v_mov_b32_e32 v53, v63
	v_mov_b32_e32 v57, v62
	s_and_b64 vcc, exec, s[6:7]
	global_store_dword v44, v50, s[100:101]
	s_add_u32 s100, s100, 0x2c00
	s_addc_u32 s101, s101, 0
	s_cbranch_vccnz .LBB0_783
	s_add_i32 s68, s81, s83
	s_addk_i32 s68, 0xc003
	s_ashr_i32 s68, s68, 2
	s_mul_hi_i32 s69, s68, 0xb000
	s_mul_i32 s68, s68, 0xb000
	s_add_u32 s68, s33, s68
	s_addc_u32 s69, s35, s69
	v_lshl_add_u64 v[48:49], v[2:3], 2, s[68:69]
	v_add_co_u32_e32 v50, vcc, 0x5000, v48
	s_nop 1
	v_addc_co_u32_e32 v51, vcc, 0, v49, vcc
	v_add_co_u32_e32 v48, vcc, 0x8000, v48
	global_store_dwordx2 v[50:51], v[52:53], off offset:2048
	s_nop 0
	v_addc_co_u32_e32 v49, vcc, 0, v49, vcc
	global_store_dwordx2 v[48:49], v[56:57], off offset:1024

; __device__ __forceinline__ float bf2f(unsigned b) { return __uint_as_float(b << 16); }
; __device__ __forceinline__ unsigned pk2(float lo, float hi) { unsigned r; asm("v_cvt_pk_bf16_f32 %0, %1, %2" : "=v"(r) : "v"(lo), "v"(hi)); return r; }
; __device__ __forceinline__ float gelu_t(float x) { return x * __builtin_amdgcn_rcpf(1.f + __expf(-1.5957691216057308f * (x + 0.044715f * x * x * x))); }
; __device__ __forceinline__ void act_item(int item, u16* UP, const u16* HALO, const float* sconv, const float* wconv, const float* bconv, float* out, int lane) {
;     ...
; #pragma unroll
;         for (int t = 0; t < 16; ++t) {
;             const int row = rb * 64 + tb + t;
;             if (sample && (t & 3) == 0) { const int ns = (row - TP) >> 2; const float* s0 = sconv + (size_t)ns * 2 * FF2;
;                 const f32x2 a = *(const f32x2*)(s0 + j0), b = *(const f32x2*)(s0 + FF + j0), c = *(const f32x2*)(s0 + FF2 + j0), dd = *(const f32x2*)(s0 + FF2 + FF + j0);
;                 g2[0] = a.x; g2[1] = a.y; v2[0] = b.x; v2[1] = b.y; g1[0] = c.x; g1[1] = c.y; v1[0] = dd.x; v1[1] = dd.y; }
;             const float g0[2] = {bf2f(gw[t] & 0xffffu), bf2f(gw[t] >> 16)}, v0[2] = {bf2f(vw[t] & 0xffffu), bf2f(vw[t] >> 16)};
;             float res[2];
; #pragma unroll
;             for (int p = 0; p < 2; ++p) { const float cgv = bg[p] + wgt[0][p] * g2[p] + wgt[1][p] * g1[p] + wgt[2][p] * g0[p];
;                 const float cvv = bv[p] + wvl[0][p] * v2[p] + wvl[1][p] * v1[p] + wvl[2][p] * v0[p]; res[p] = gelu_t(cgv) * cvv;
;                 g2[p] = g1[p]; g1[p] = g0[p]; v2[p] = v1[p]; v1[p] = v0[p]; }
;             *(unsigned*)(UP + (size_t)row * FF2 + j0) = pk2(res[0], res[1]);
.LBB0_785:
	v_pk_fma_f32 v[48:49], v[4:5], v[58:59], v[16:17]
	v_lshlrev_b32_e32 v62, 16, v86
	v_pk_fma_f32 v[48:49], v[8:9], v[52:53], v[48:49]
	v_and_b32_e32 v63, 0xffff0000, v86
	v_fma_f32 v48, v12, v62, v48
	v_mul_f32_e32 v54, 0x3d372713, v48
	v_fmac_f32_e32 v49, v13, v63
	v_mul_f32_e32 v54, v48, v54
	v_mul_f32_e32 v55, 0x3d372713, v49
	v_fma_f32 v54, v48, v54, v48
	v_mul_f32_e32 v55, v49, v55
	v_mul_f32_e32 v54, 0xbfcc422a, v54
	v_fma_f32 v55, v49, v55, v49
	v_mul_f32_e32 v54, 0x3fb8aa3b, v54
	v_mul_f32_e32 v55, 0xbfcc422a, v55
	v_exp_f32_e32 v54, v54
	v_mul_f32_e32 v55, 0x3fb8aa3b, v55
	v_exp_f32_e32 v55, v55
	v_pk_fma_f32 v[50:51], v[6:7], v[60:61], v[18:19]
	v_add_f32_e32 v54, 1.0, v54
	v_rcp_f32_e32 v54, v54
	v_add_f32_e32 v55, 1.0, v55
	v_rcp_f32_e32 v55, v55
	v_lshlrev_b32_e32 v86, 16, v85
	v_pk_fma_f32 v[50:51], v[10:11], v[56:57], v[50:51]
	v_and_b32_e32 v85, 0xffff0000, v85
	v_fma_f32 v50, v14, v86, v50
	v_mul_f32_e32 v48, v48, v54
	v_mul_f32_e32 v48, v50, v48
	v_fmac_f32_e32 v51, v15, v85
	v_mul_f32_e32 v49, v49, v55
	v_mul_f32_e32 v49, v51, v49
	v_cvt_pk_bf16_f32 v50, v48, v49
	v_pk_fma_f32 v[58:59], v[4:5], v[52:53], v[16:17]
	v_lshlrev_b32_e32 v51, 16, v83
	v_fma_f32 v58, v8, v62, v58
	global_store_dword v44, v50, s[100:101]
	s_add_u32 s100, s100, 0x2c00
	s_addc_u32 s101, s101, 0
	v_and_b32_e32 v49, 0xffff0000, v83
	v_fmac_f32_e32 v59, v9, v63
	v_fmac_f32_e32 v58, v12, v51
	v_mul_f32_e32 v60, 0x3d372713, v58
	v_fmac_f32_e32 v59, v13, v49
	v_mul_f32_e32 v60, v58, v60
	v_mul_f32_e32 v61, 0x3d372713, v59
	v_fma_f32 v60, v58, v60, v58
	v_mul_f32_e32 v61, v59, v61
	v_mul_f32_e32 v60, 0xbfcc422a, v60
	v_fma_f32 v61, v59, v61, v59
	v_mul_f32_e32 v60, 0x3fb8aa3b, v60
	v_mul_f32_e32 v61, 0xbfcc422a, v61
	v_exp_f32_e32 v60, v60
	v_mul_f32_e32 v61, 0x3fb8aa3b, v61
	v_exp_f32_e32 v61, v61
	v_pk_fma_f32 v[56:57], v[6:7], v[56:57], v[18:19]
	v_add_f32_e32 v60, 1.0, v60
	v_rcp_f32_e32 v60, v60
	v_add_f32_e32 v61, 1.0, v61
	v_rcp_f32_e32 v61, v61
	v_lshlrev_b32_e32 v50, 16, v84
	v_fma_f32 v56, v10, v86, v56
	v_fmac_f32_e32 v56, v14, v50
	v_mul_f32_e32 v58, v58, v60
	v_mul_f32_e32 v56, v56, v58
	v_mul_f32_e32 v58, v59, v61
	v_fma_f32 v59, v4, v62, v16
	v_lshlrev_b32_e32 v55, 16, v81
	v_fmac_f32_e32 v59, v8, v51
	v_fmac_f32_e32 v59, v12, v55
	v_mul_f32_e32 v60, 0x3d372713, v59
	v_mul_f32_e32 v60, v59, v60
	v_and_b32_e32 v48, 0xffff0000, v84
	v_fmac_f32_e32 v57, v11, v85
	v_fma_f32 v60, v59, v60, v59
	v_fmac_f32_e32 v57, v40, v48
	v_mul_f32_e32 v60, 0xbfcc422a, v60
	v_mul_f32_e32 v57, v57, v58
	v_cvt_pk_bf16_f32 v58, v56, v57
	v_mul_f32_e32 v60, 0x3fb8aa3b, v60
	v_exp_f32_e32 v60, v60
	global_store_dword v44, v58, s[100:101]
	s_add_u32 s100, s100, 0x2c00
	s_addc_u32 s101, s101, 0
	v_fma_f32 v58, v5, v63, v17
	v_and_b32_e32 v53, 0xffff0000, v81
	v_fmac_f32_e32 v58, v9, v49
	v_fmac_f32_e32 v58, v13, v53
	v_add_f32_e32 v57, 1.0, v60
	v_mul_f32_e32 v60, 0x3d372713, v58
	v_mul_f32_e32 v60, v58, v60
	v_fma_f32 v60, v58, v60, v58
	v_mul_f32_e32 v60, 0xbfcc422a, v60
	v_rcp_f32_e32 v57, v57
	v_mul_f32_e32 v60, 0x3fb8aa3b, v60
	v_exp_f32_e32 v60, v60
	v_fma_f32 v56, v6, v86, v18
	v_lshlrev_b32_e32 v54, 16, v82
	v_fmac_f32_e32 v56, v10, v50
	v_fmac_f32_e32 v56, v14, v54
	v_mul_f32_e32 v57, v59, v57
	v_mul_f32_e32 v56, v56, v57
	v_add_f32_e32 v57, 1.0, v60
	v_rcp_f32_e32 v57, v57
	v_fma_f32 v59, v7, v85, v19
	v_and_b32_e32 v52, 0xffff0000, v82
	v_fmac_f32_e32 v59, v42, v48
	v_fmac_f32_e32 v59, v40, v52
	v_mul_f32_e32 v57, v58, v57
	v_mul_f32_e32 v57, v59, v57
	v_cvt_pk_bf16_f32 v58, v56, v57
	v_mov_b32_e32 v59, v52
	global_store_dword v44, v58, s[100:101]
	s_add_u32 s100, s100, 0x2c00
	s_addc_u32 s101, s101, 0
	v_mov_b32_e32 v58, v54
	v_mov_b32_e32 v62, v55
	v_mov_b32_e32 v63, v53
	s_mov_b64 s[68:69], -1
	s_and_b64 vcc, exec, s[0:1]
	v_mov_b64_e32 v[56:57], v[62:63]
	v_mov_b64_e32 v[60:61], v[58:59]
	s_cbranch_vccnz .LBB0_787
	v_mov_b32_e32 v56, v55
	v_mov_b32_e32 v57, v53
	v_mov_b32_e32 v60, v54
	v_mov_b32_e32 v61, v52
	s_mov_b64 s[68:69], 0

; __device__ __forceinline__ unsigned pk2(float lo, float hi) { unsigned r; asm("v_cvt_pk_bf16_f32 %0, %1, %2" : "=v"(r) : "v"(lo), "v"(hi)); return r; }
; __device__ __forceinline__ float gelu_t(float x) { return x * __builtin_amdgcn_rcpf(1.f + __expf(-1.5957691216057308f * (x + 0.044715f * x * x * x))); }
; __device__ __forceinline__ void act_item(int item, u16* UP, const u16* HALO, const float* sconv, const float* wconv, const float* bconv, float* out, int lane) {
;     ...
;             for (int p = 0; p < 2; ++p) { const float cgv = bg[p] + wgt[0][p] * g2[p] + wgt[1][p] * g1[p] + wgt[2][p] * g0[p];
;                 const float cvv = bv[p] + wvl[0][p] * v2[p] + wvl[1][p] * v1[p] + wvl[2][p] * v0[p]; res[p] = gelu_t(cgv) * cvv;
;                 g2[p] = g1[p]; g1[p] = g0[p]; v2[p] = v1[p]; v1[p] = v0[p]; }
;             *(unsigned*)(UP + (size_t)row * FF2 + j0) = pk2(res[0], res[1]);
;             if (!sample) { const int tq = row & 2047; if (tq >= 2046) { float* o = out + O_CONVP + ((size_t)(row >> 11) * 2 + (tq - 2046)) * FF2;
;                     *(f32x2*)(o + j0) = (f32x2){g0[0], g0[1]}; *(f32x2*)(o + FF + j0) = (f32x2){v0[0], v0[1]}; } }
;             else if ((t & 3) >= 2) { const int ns = (row - TP) >> 2; float* o = out + O_CONVS + ((size_t)ns * 2 + ((t & 3) - 2)) * FF2;
;                     *(f32x2*)(o + j0) = (f32x2){g0[0], g0[1]}; *(f32x2*)(o + FF + j0) = (f32x2){v0[0], v0[1]}; }
.LBB0_789:
	v_pk_fma_f32 v[48:49], v[34:35], v[48:49], v[32:33]
	v_and_b32_e32 v63, 0xffff0000, v79
	v_and_b32_e32 v62, 0xffff0000, v80
	v_pk_fma_f32 v[50:51], v[26:27], v[50:51], v[24:25]
	v_pk_fma_f32 v[48:49], v[36:37], v[52:53], v[48:49]
	v_lshlrev_b32_e32 v59, 16, v79
	v_lshlrev_b32_e32 v58, 16, v80
	v_pk_fma_f32 v[50:51], v[28:29], v[54:55], v[50:51]
	v_pk_fma_f32 v[48:49], v[38:39], v[62:63], v[48:49]
	v_pk_fma_f32 v[50:51], v[30:31], v[58:59], v[50:51]
	v_mul_f32_e32 v52, 0x3d372713, v49
	v_mul_f32_e32 v54, 0x3d372713, v51
	v_mul_f32_e32 v52, v49, v52
	v_mul_f32_e32 v54, v51, v54
	v_fma_f32 v52, v49, v52, v49
	v_fma_f32 v54, v51, v54, v51
	v_mul_f32_e32 v52, 0xbfcc422a, v52
	v_mul_f32_e32 v54, 0xbfcc422a, v54
	v_mul_f32_e32 v52, 0x3fb8aa3b, v52
	v_mul_f32_e32 v54, 0x3fb8aa3b, v54
	v_exp_f32_e32 v52, v52
	v_exp_f32_e32 v54, v54
	v_add_f32_e32 v52, 1.0, v52
	v_add_f32_e32 v53, 1.0, v54
	v_rcp_f32_e32 v52, v52
	v_rcp_f32_e32 v53, v53
	v_mul_f32_e32 v49, v49, v52
	v_mul_f32_e32 v51, v51, v53
	v_mul_f32_e32 v48, v48, v49
	v_mul_f32_e32 v53, v50, v51
	v_cvt_pk_bf16_f32 v52, v53, v48
	v_mov_b32_e32 v50, v59
	v_mov_b32_e32 v51, v63
	v_mov_b32_e32 v59, v62
	s_and_b64 vcc, exec, s[6:7]
	global_store_dword v44, v52, s[100:101]
	s_add_u32 s100, s100, 0x2c00
	s_addc_u32 s101, s101, 0
	s_cbranch_vccnz .LBB0_791
	s_add_i32 s68, s81, s83
	s_addk_i32 s68, 0xc007
	s_ashr_i32 s68, s68, 2
	s_mul_hi_i32 s69, s68, 0xb000
	s_mul_i32 s68, s68, 0xb000
	s_add_u32 s68, s33, s68
	s_addc_u32 s69, s35, s69
	v_lshl_add_u64 v[48:49], v[2:3], 2, s[68:69]
	v_add_co_u32_e32 v52, vcc, 0x5000, v48
	s_nop 1
	v_addc_co_u32_e32 v53, vcc, 0, v49, vcc
	v_add_co_u32_e32 v48, vcc, 0x8000, v48
	global_store_dwordx2 v[52:53], v[50:51], off offset:2048
	s_nop 0
	v_addc_co_u32_e32 v49, vcc, 0, v49, vcc
	global_store_dwordx2 v[48:49], v[58:59], off offset:1024

; __device__ __forceinline__ float bf2f(unsigned b) { return __uint_as_float(b << 16); }
; __device__ __forceinline__ unsigned pk2(float lo, float hi) { unsigned r; asm("v_cvt_pk_bf16_f32 %0, %1, %2" : "=v"(r) : "v"(lo), "v"(hi)); return r; }
; __device__ __forceinline__ float gelu_t(float x) { return x * __builtin_amdgcn_rcpf(1.f + __expf(-1.5957691216057308f * (x + 0.044715f * x * x * x))); }
; __device__ __forceinline__ void act_item(int item, u16* UP, const u16* HALO, const float* sconv, const float* wconv, const float* bconv, float* out, int lane) {
;     ...
; #pragma unroll
;         for (int t = 0; t < 16; ++t) {
;             const int row = rb * 64 + tb + t;
;             if (sample && (t & 3) == 0) { const int ns = (row - TP) >> 2; const float* s0 = sconv + (size_t)ns * 2 * FF2;
;                 const f32x2 a = *(const f32x2*)(s0 + j0), b = *(const f32x2*)(s0 + FF + j0), c = *(const f32x2*)(s0 + FF2 + j0), dd = *(const f32x2*)(s0 + FF2 + FF + j0);
;                 g2[0] = a.x; g2[1] = a.y; v2[0] = b.x; v2[1] = b.y; g1[0] = c.x; g1[1] = c.y; v1[0] = dd.x; v1[1] = dd.y; }
;             const float g0[2] = {bf2f(gw[t] & 0xffffu), bf2f(gw[t] >> 16)}, v0[2] = {bf2f(vw[t] & 0xffffu), bf2f(vw[t] >> 16)};
;             float res[2];
; #pragma unroll
;             for (int p = 0; p < 2; ++p) { const float cgv = bg[p] + wgt[0][p] * g2[p] + wgt[1][p] * g1[p] + wgt[2][p] * g0[p];
;                 const float cvv = bv[p] + wvl[0][p] * v2[p] + wvl[1][p] * v1[p] + wvl[2][p] * v0[p]; res[p] = gelu_t(cgv) * cvv;
;                 g2[p] = g1[p]; g1[p] = g0[p]; v2[p] = v1[p]; v1[p] = v0[p]; }
;             *(unsigned*)(UP + (size_t)row * FF2 + j0) = pk2(res[0], res[1]);
.LBB0_793:
	v_pk_fma_f32 v[48:49], v[4:5], v[56:57], v[16:17]
	v_lshlrev_b32_e32 v54, 16, v78
	v_pk_fma_f32 v[48:49], v[8:9], v[50:51], v[48:49]
	v_and_b32_e32 v55, 0xffff0000, v78
	v_fma_f32 v48, v12, v54, v48
	v_mul_f32_e32 v56, 0x3d372713, v48
	v_fmac_f32_e32 v49, v13, v55
	v_mul_f32_e32 v56, v48, v56
	v_mul_f32_e32 v57, 0x3d372713, v49
	v_fma_f32 v56, v48, v56, v48
	v_mul_f32_e32 v57, v49, v57
	v_mul_f32_e32 v56, 0xbfcc422a, v56
	v_fma_f32 v57, v49, v57, v49
	v_mul_f32_e32 v56, 0x3fb8aa3b, v56
	v_mul_f32_e32 v57, 0xbfcc422a, v57
	v_exp_f32_e32 v56, v56
	v_mul_f32_e32 v57, 0x3fb8aa3b, v57
	v_exp_f32_e32 v57, v57
	v_pk_fma_f32 v[52:53], v[6:7], v[60:61], v[18:19]
	v_add_f32_e32 v56, 1.0, v56
	v_rcp_f32_e32 v56, v56
	v_add_f32_e32 v57, 1.0, v57
	v_rcp_f32_e32 v57, v57
	v_lshlrev_b32_e32 v62, 16, v77
	v_pk_fma_f32 v[52:53], v[10:11], v[58:59], v[52:53]
	v_and_b32_e32 v63, 0xffff0000, v77
	v_fma_f32 v52, v14, v62, v52
	v_mul_f32_e32 v48, v48, v56
	v_mul_f32_e32 v48, v52, v48
	v_fmac_f32_e32 v53, v15, v63
	v_mul_f32_e32 v49, v49, v57
	v_mul_f32_e32 v49, v53, v49
	v_cvt_pk_bf16_f32 v52, v48, v49
	v_pk_fma_f32 v[50:51], v[4:5], v[50:51], v[16:17]
	global_store_dword v44, v52, s[100:101]
	s_add_u32 s100, s100, 0x2c00
	s_addc_u32 s101, s101, 0
	v_and_b32_e32 v49, 0xffff0000, v75
	v_fmac_f32_e32 v51, v9, v55
	v_fmac_f32_e32 v51, v13, v49
	v_pk_fma_f32 v[52:53], v[6:7], v[58:59], v[18:19]
	v_lshlrev_b32_e32 v60, 16, v74
	v_and_b32_e32 v58, 0xffff0000, v74
	v_mul_f32_e32 v74, 0x3d372713, v51
	v_mul_f32_e32 v74, v51, v74
	v_fma_f32 v74, v51, v74, v51
	v_mul_f32_e32 v74, 0xbfcc422a, v74
	v_lshlrev_b32_e32 v57, 16, v75
	v_fma_f32 v50, v8, v54, v50
	v_mul_f32_e32 v74, 0x3fb8aa3b, v74
	v_fmac_f32_e32 v50, v12, v57
	v_exp_f32_e32 v74, v74
	v_lshlrev_b32_e32 v61, 16, v73
	v_and_b32_e32 v59, 0xffff0000, v73
	v_mul_f32_e32 v73, 0x3d372713, v50
	v_mul_f32_e32 v73, v50, v73
	v_fma_f32 v73, v50, v73, v50
	v_mul_f32_e32 v73, 0xbfcc422a, v73
	v_add_f32_e32 v74, 1.0, v74
	v_mul_f32_e32 v73, 0x3fb8aa3b, v73
	v_rcp_f32_e32 v74, v74
	v_exp_f32_e32 v73, v73
	v_and_b32_e32 v48, 0xffff0000, v76
	v_fmac_f32_e32 v53, v11, v63
	v_fmac_f32_e32 v53, v40, v48
	v_mul_f32_e32 v51, v51, v74
	v_add_f32_e32 v73, 1.0, v73
	v_mul_f32_e32 v51, v53, v51
	v_fma_f32 v53, v4, v54, v16
	v_rcp_f32_e32 v73, v73
	v_fmac_f32_e32 v53, v8, v57
	v_fmac_f32_e32 v53, v12, v61
	v_mul_f32_e32 v54, 0x3d372713, v53
	v_lshlrev_b32_e32 v56, 16, v76
	v_fma_f32 v52, v10, v62, v52
	v_mul_f32_e32 v54, v53, v54
	v_fmac_f32_e32 v52, v14, v56
	v_mul_f32_e32 v50, v50, v73
	v_fma_f32 v54, v53, v54, v53
	v_mul_f32_e32 v50, v52, v50
	v_mul_f32_e32 v54, 0xbfcc422a, v54
	v_cvt_pk_bf16_f32 v52, v50, v51
	v_mul_f32_e32 v54, 0x3fb8aa3b, v54
	v_exp_f32_e32 v54, v54
	global_store_dword v44, v52, s[100:101]
	s_add_u32 s100, s100, 0x2c00
	s_addc_u32 s101, s101, 0
	v_fma_f32 v52, v5, v55, v17
	v_fmac_f32_e32 v52, v9, v49
	v_fmac_f32_e32 v52, v13, v59
	v_add_f32_e32 v51, 1.0, v54
	v_mul_f32_e32 v54, 0x3d372713, v52
	v_mul_f32_e32 v54, v52, v54
	v_fma_f32 v54, v52, v54, v52
	v_mul_f32_e32 v54, 0xbfcc422a, v54
	v_rcp_f32_e32 v51, v51
	v_mul_f32_e32 v54, 0x3fb8aa3b, v54
	v_exp_f32_e32 v54, v54
	v_fma_f32 v50, v6, v62, v18
	v_fmac_f32_e32 v50, v10, v56
	v_fmac_f32_e32 v50, v14, v60
	v_mul_f32_e32 v51, v53, v51
	v_mul_f32_e32 v50, v50, v51
	v_add_f32_e32 v51, 1.0, v54
	v_rcp_f32_e32 v51, v51
	v_fma_f32 v53, v7, v63, v19
	v_fmac_f32_e32 v53, v42, v48
	v_fmac_f32_e32 v53, v40, v58
	v_mul_f32_e32 v51, v52, v51
	v_mul_f32_e32 v51, v53, v51
	v_cvt_pk_bf16_f32 v52, v50, v51
	v_mov_b32_e32 v62, v61
	global_store_dword v44, v52, s[100:101]
	s_add_u32 s100, s100, 0x2c00
	s_addc_u32 s101, s101, 0
	v_mov_b32_e32 v50, v60
	v_mov_b32_e32 v51, v58
	v_mov_b32_e32 v63, v59
	s_mov_b64 s[68:69], -1
	s_and_b64 vcc, exec, s[0:1]
	v_mov_b64_e32 v[52:53], v[62:63]
	v_mov_b64_e32 v[54:55], v[50:51]
	s_cbranch_vccnz .LBB0_795
	v_mov_b32_e32 v52, v61
	v_mov_b32_e32 v53, v59
	v_mov_b32_e32 v54, v60
	v_mov_b32_e32 v55, v58
	s_mov_b64 s[68:69], 0

; __device__ __forceinline__ unsigned pk2(float lo, float hi) { unsigned r; asm("v_cvt_pk_bf16_f32 %0, %1, %2" : "=v"(r) : "v"(lo), "v"(hi)); return r; }
; __device__ __forceinline__ float gelu_t(float x) { return x * __builtin_amdgcn_rcpf(1.f + __expf(-1.5957691216057308f * (x + 0.044715f * x * x * x))); }
; __device__ __forceinline__ void act_item(int item, u16* UP, const u16* HALO, const float* sconv, const float* wconv, const float* bconv, float* out, int lane) {
;     ...
;             for (int p = 0; p < 2; ++p) { const float cgv = bg[p] + wgt[0][p] * g2[p] + wgt[1][p] * g1[p] + wgt[2][p] * g0[p];
;                 const float cvv = bv[p] + wvl[0][p] * v2[p] + wvl[1][p] * v1[p] + wvl[2][p] * v0[p]; res[p] = gelu_t(cgv) * cvv;
;                 g2[p] = g1[p]; g1[p] = g0[p]; v2[p] = v1[p]; v1[p] = v0[p]; }
;             *(unsigned*)(UP + (size_t)row * FF2 + j0) = pk2(res[0], res[1]);
;             if (!sample) { const int tq = row & 2047; if (tq >= 2046) { float* o = out + O_CONVP + ((size_t)(row >> 11) * 2 + (tq - 2046)) * FF2;
;                     *(f32x2*)(o + j0) = (f32x2){g0[0], g0[1]}; *(f32x2*)(o + FF + j0) = (f32x2){v0[0], v0[1]}; } }
;             else if ((t & 3) >= 2) { const int ns = (row - TP) >> 2; float* o = out + O_CONVS + ((size_t)ns * 2 + ((t & 3) - 2)) * FF2;
;                     *(f32x2*)(o + j0) = (f32x2){g0[0], g0[1]}; *(f32x2*)(o + FF + j0) = (f32x2){v0[0], v0[1]}; }
.LBB0_797:
	v_pk_fma_f32 v[56:57], v[26:27], v[56:57], v[24:25]
	v_lshlrev_b32_e32 v51, 16, v71
	v_lshlrev_b32_e32 v50, 16, v72
	v_pk_fma_f32 v[56:57], v[28:29], v[60:61], v[56:57]
	v_pk_fma_f32 v[48:49], v[34:35], v[48:49], v[32:33]
	v_and_b32_e32 v63, 0xffff0000, v71
	v_and_b32_e32 v62, 0xffff0000, v72
	v_pk_fma_f32 v[56:57], v[30:31], v[50:51], v[56:57]
	v_pk_fma_f32 v[48:49], v[36:37], v[58:59], v[48:49]
	v_mul_f32_e32 v60, 0x3d372713, v57
	v_pk_fma_f32 v[48:49], v[38:39], v[62:63], v[48:49]
	v_mul_f32_e32 v60, v57, v60
	v_mul_f32_e32 v58, 0x3d372713, v49
	v_fma_f32 v60, v57, v60, v57
	v_mul_f32_e32 v58, v49, v58
	v_mul_f32_e32 v60, 0xbfcc422a, v60
	v_fma_f32 v58, v49, v58, v49
	v_mul_f32_e32 v60, 0x3fb8aa3b, v60
	v_mul_f32_e32 v58, 0xbfcc422a, v58
	v_exp_f32_e32 v60, v60
	v_mul_f32_e32 v58, 0x3fb8aa3b, v58
	v_exp_f32_e32 v58, v58
	v_add_f32_e32 v59, 1.0, v60
	v_rcp_f32_e32 v59, v59
	v_add_f32_e32 v58, 1.0, v58
	v_rcp_f32_e32 v58, v58
	v_mul_f32_e32 v57, v57, v59
	v_mul_f32_e32 v56, v56, v57
	v_mul_f32_e32 v49, v49, v58
	v_mul_f32_e32 v57, v48, v49
	v_cvt_pk_bf16_f32 v58, v56, v57
	v_mov_b32_e32 v48, v51
	v_mov_b32_e32 v49, v63
	v_mov_b32_e32 v51, v62
	s_and_b64 vcc, exec, s[6:7]
	global_store_dword v44, v58, s[100:101]
	s_add_u32 s100, s100, 0x2c00
	s_addc_u32 s101, s101, 0
	s_cbranch_vccnz .LBB0_812
	s_add_i32 s6, s81, s83
	s_addk_i32 s6, 0xc00b
	s_ashr_i32 s6, s6, 2
	s_mul_hi_i32 s7, s6, 0xb000
	s_mul_i32 s6, s6, 0xb000
	s_add_u32 s6, s33, s6
	s_addc_u32 s7, s35, s7
	v_lshl_add_u64 v[56:57], v[2:3], 2, s[6:7]
	v_add_co_u32_e32 v58, vcc, 0x5000, v56
	s_nop 1
	v_addc_co_u32_e32 v59, vcc, 0, v57, vcc
	v_add_co_u32_e32 v56, vcc, 0x8000, v56
	global_store_dwordx2 v[58:59], v[48:49], off offset:2048
	s_nop 0
	v_addc_co_u32_e32 v57, vcc, 0, v57, vcc
	global_store_dwordx2 v[56:57], v[50:51], off offset:1024
	s_and_b64 vcc, exec, s[0:1]
	s_mov_b64 s[6:7], -1
	s_cbranch_vccz .LBB0_813

; __device__ __forceinline__ float bf2f(unsigned b) { return __uint_as_float(b << 16); }
; __device__ __forceinline__ unsigned pk2(float lo, float hi) { unsigned r; asm("v_cvt_pk_bf16_f32 %0, %1, %2" : "=v"(r) : "v"(lo), "v"(hi)); return r; }
; __device__ __forceinline__ float gelu_t(float x) { return x * __builtin_amdgcn_rcpf(1.f + __expf(-1.5957691216057308f * (x + 0.044715f * x * x * x))); }
; __device__ __forceinline__ void act_item(int item, u16* UP, const u16* HALO, const float* sconv, const float* wconv, const float* bconv, float* out, int lane) {
;     ...
;         for (int t = 0; t < 16; ++t) {
;             const int row = rb * 64 + tb + t;
;             if (sample && (t & 3) == 0) { const int ns = (row - TP) >> 2; const float* s0 = sconv + (size_t)ns * 2 * FF2;
;                 const f32x2 a = *(const f32x2*)(s0 + j0), b = *(const f32x2*)(s0 + FF + j0), c = *(const f32x2*)(s0 + FF2 + j0), dd = *(const f32x2*)(s0 + FF2 + FF + j0);
;                 g2[0] = a.x; g2[1] = a.y; v2[0] = b.x; v2[1] = b.y; g1[0] = c.x; g1[1] = c.y; v1[0] = dd.x; v1[1] = dd.y; }
;             const float g0[2] = {bf2f(gw[t] & 0xffffu), bf2f(gw[t] >> 16)}, v0[2] = {bf2f(vw[t] & 0xffffu), bf2f(vw[t] >> 16)};
;             float res[2];
; #pragma unroll
;             for (int p = 0; p < 2; ++p) { const float cgv = bg[p] + wgt[0][p] * g2[p] + wgt[1][p] * g1[p] + wgt[2][p] * g0[p];
;                 const float cvv = bv[p] + wvl[0][p] * v2[p] + wvl[1][p] * v1[p] + wvl[2][p] * v0[p]; res[p] = gelu_t(cgv) * cvv;
;                 g2[p] = g1[p]; g1[p] = g0[p]; v2[p] = v1[p]; v1[p] = v0[p]; }
;             *(unsigned*)(UP + (size_t)row * FF2 + j0) = pk2(res[0], res[1]);
.LBB0_801:
	v_pk_fma_f32 v[52:53], v[4:5], v[52:53], v[16:17]
	v_lshlrev_b32_e32 v71, 16, v70
	v_pk_fma_f32 v[52:53], v[8:9], v[48:49], v[52:53]
	v_and_b32_e32 v70, 0xffff0000, v70
	v_fma_f32 v52, v12, v71, v52
	v_mul_f32_e32 v56, 0x3d372713, v52
	v_fmac_f32_e32 v53, v13, v70
	v_mul_f32_e32 v56, v52, v56
	v_mul_f32_e32 v57, 0x3d372713, v53
	v_fma_f32 v56, v52, v56, v52
	v_mul_f32_e32 v57, v53, v57
	v_mul_f32_e32 v56, 0xbfcc422a, v56
	v_fma_f32 v57, v53, v57, v53
	v_mul_f32_e32 v56, 0x3fb8aa3b, v56
	v_mul_f32_e32 v57, 0xbfcc422a, v57
	v_exp_f32_e32 v56, v56
	v_mul_f32_e32 v57, 0x3fb8aa3b, v57
	v_exp_f32_e32 v57, v57
	v_pk_fma_f32 v[54:55], v[6:7], v[54:55], v[18:19]
	v_add_f32_e32 v56, 1.0, v56
	v_rcp_f32_e32 v56, v56
	v_add_f32_e32 v57, 1.0, v57
	v_rcp_f32_e32 v57, v57
	v_lshlrev_b32_e32 v72, 16, v69
	v_pk_fma_f32 v[54:55], v[10:11], v[50:51], v[54:55]
	v_and_b32_e32 v69, 0xffff0000, v69
	v_fma_f32 v54, v14, v72, v54
	v_mul_f32_e32 v52, v52, v56
	v_mul_f32_e32 v52, v54, v52
	v_fmac_f32_e32 v55, v15, v69
	v_mul_f32_e32 v53, v53, v57
	v_pk_fma_f32 v[48:49], v[4:5], v[48:49], v[16:17]
	v_mul_f32_e32 v53, v55, v53
	v_cvt_pk_bf16_f32 v54, v52, v53
	v_and_b32_e32 v57, 0xffff0000, v66
	v_fmac_f32_e32 v49, v9, v70
	v_fmac_f32_e32 v49, v13, v57
	global_store_dword v44, v54, s[100:101]
	s_add_u32 s100, s100, 0x2c00
	s_addc_u32 s101, s101, 0
	v_mul_f32_e32 v53, 0x3d372713, v49
	v_mul_f32_e32 v53, v49, v53
	v_lshlrev_b32_e32 v59, 16, v66
	v_fma_f32 v48, v8, v71, v48
	v_fma_f32 v53, v49, v53, v49
	v_fmac_f32_e32 v48, v12, v59
	v_mul_f32_e32 v53, 0xbfcc422a, v53
	v_mul_f32_e32 v52, 0x3d372713, v48
	v_mul_f32_e32 v53, 0x3fb8aa3b, v53
	v_mul_f32_e32 v52, v48, v52
	v_exp_f32_e32 v53, v53
	v_fma_f32 v52, v48, v52, v48
	v_mul_f32_e32 v52, 0xbfcc422a, v52
	v_mul_f32_e32 v52, 0x3fb8aa3b, v52
	v_exp_f32_e32 v52, v52
	v_add_f32_e32 v53, 1.0, v53
	v_rcp_f32_e32 v53, v53
	v_pk_fma_f32 v[50:51], v[6:7], v[50:51], v[18:19]
	v_and_b32_e32 v56, 0xffff0000, v67
	v_fmac_f32_e32 v51, v11, v69
	v_add_f32_e32 v52, 1.0, v52
	v_rcp_f32_e32 v52, v52
	v_fmac_f32_e32 v51, v40, v56
	v_mul_f32_e32 v49, v49, v53
	v_mul_f32_e32 v49, v51, v49
	v_fma_f32 v51, v4, v71, v16
	v_lshlrev_b32_e32 v63, 16, v64
	v_fmac_f32_e32 v51, v8, v59
	v_fmac_f32_e32 v51, v12, v63
	v_mul_f32_e32 v48, v48, v52
	v_mul_f32_e32 v52, 0x3d372713, v51
	v_lshlrev_b32_e32 v58, 16, v67
	v_fma_f32 v50, v10, v72, v50
	v_mul_f32_e32 v52, v51, v52
	v_fmac_f32_e32 v50, v14, v58
	v_fma_f32 v52, v51, v52, v51
	v_mul_f32_e32 v48, v50, v48
	v_mul_f32_e32 v52, 0xbfcc422a, v52
	v_cvt_pk_bf16_f32 v50, v48, v49
	v_mul_f32_e32 v52, 0x3fb8aa3b, v52
	v_exp_f32_e32 v52, v52
	global_store_dword v44, v50, s[100:101]
	s_add_u32 s100, s100, 0x2c00
	s_addc_u32 s101, s101, 0
	v_fma_f32 v50, v5, v70, v17
	v_and_b32_e32 v61, 0xffff0000, v64
	v_fmac_f32_e32 v50, v9, v57
	v_fmac_f32_e32 v50, v13, v61
	v_add_f32_e32 v49, 1.0, v52
	v_mul_f32_e32 v52, 0x3d372713, v50
	v_mul_f32_e32 v52, v50, v52
	v_fma_f32 v52, v50, v52, v50
	v_mul_f32_e32 v52, 0xbfcc422a, v52
	v_rcp_f32_e32 v49, v49
	v_mul_f32_e32 v52, 0x3fb8aa3b, v52
	v_exp_f32_e32 v52, v52
	v_fma_f32 v48, v6, v72, v18
	v_lshlrev_b32_e32 v62, 16, v65
	v_fmac_f32_e32 v48, v10, v58
	v_fmac_f32_e32 v48, v14, v62
	v_mul_f32_e32 v49, v51, v49
	v_mul_f32_e32 v48, v48, v49
	v_add_f32_e32 v49, 1.0, v52
	v_rcp_f32_e32 v49, v49
	v_fma_f32 v51, v7, v69, v19
	v_and_b32_e32 v60, 0xffff0000, v65
	v_fmac_f32_e32 v51, v42, v56
	v_fmac_f32_e32 v51, v40, v60
	v_mul_f32_e32 v49, v50, v49
	v_mul_f32_e32 v49, v51, v49
	v_cvt_pk_bf16_f32 v50, v48, v49
	v_mov_b32_e32 v52, v62
	v_mov_b32_e32 v53, v60
	v_mov_b32_e32 v54, v63
	v_mov_b32_e32 v55, v61
	global_store_dword v44, v50, s[100:101]
	s_add_u32 s100, s100, 0x2c00
	s_addc_u32 s101, s101, 0
	s_mov_b64 s[6:7], -1
	s_and_b64 vcc, exec, s[0:1]
	v_mov_b64_e32 v[48:49], v[54:55]
	v_mov_b64_e32 v[50:51], v[52:53]
	s_cbranch_vccnz .LBB0_807
	s_add_i32 s6, s84, 14
	s_and_b32 s6, s6, 0x7fe
	v_mov_b32_e32 v64, v62
	v_mov_b32_e32 v65, v60
	v_mov_b32_e32 v66, v63
	v_mov_b32_e32 v67, v61
	s_cmpk_eq_i32 s6, 0x7fe
	s_mov_b64 s[6:7], -1
	v_mov_b64_e32 v[48:49], v[66:67]
	v_mov_b64_e32 v[50:51], v[64:65]
	s_cbranch_scc1 .LBB0_804
	v_mov_b32_e32 v48, v63
	v_mov_b32_e32 v49, v61
	v_mov_b32_e32 v50, v62
	v_mov_b32_e32 v51, v60
	s_mov_b64 s[6:7], 0
